# row passes: nt cache policy on once-read streaming loads (x, Y, stash, split-K partials)
# speedup vs baseline: 1.0136x; 1.0136x over previous
.LBB0_360:
	s_or_b64 exec, exec, s[0:1]
	v_readlane_b32 s8, v247, 1
	v_add_u32_e32 v1, 0xffff8000, v64
	v_cmp_gt_i32_e32 vcc, s3, v64
	v_readlane_b32 s9, v247, 2
	v_readlane_b32 s13, v247, 6
	v_ashrrev_i32_e32 v65, 31, v64
	v_cndmask_b32_e32 v2, v1, v64, vcc
	v_readlane_b32 s12, v247, 5
	v_mov_b32_e32 v1, s13
	v_mov_b32_e32 v36, s9
	v_cndmask_b32_e32 v3, 0, v65, vcc
	v_cndmask_b32_e32 v37, v1, v36, vcc
	v_mov_b32_e32 v1, s12
	v_mov_b32_e32 v36, s8
	v_cndmask_b32_e32 v36, v1, v36, vcc
	v_lshlrev_b64 v[2:3], 12, v[2:3]
	v_lshl_add_u64 v[2:3], v[36:37], 0, v[2:3]
	v_lshl_add_u64 v[2:3], v[2:3], 0, v[66:67]
	global_load_dwordx4 v[60:63], v[2:3], off nt
	global_load_dwordx4 v[56:59], v[2:3], off offset:1024 nt
	global_load_dwordx4 v[52:55], v[2:3], off offset:2048 nt
	global_load_dwordx4 v[48:51], v[2:3], off offset:3072 nt
	v_add_u32_e32 v76, 1, v64
	v_cmp_lt_i32_e32 vcc, v76, v82
	v_ashrrev_i32_e32 v77, 31, v76
	v_mov_b32_e32 v1, 0
	v_mov_b32_e32 v2, 0
	v_mov_b32_e32 v3, 0
	v_mov_b32_e32 v44, 0
	v_mov_b32_e32 v45, 0
	v_mov_b32_e32 v46, 0
	v_mov_b32_e32 v47, 0
	v_mov_b32_e32 v40, 0
	v_mov_b32_e32 v41, 0
	v_mov_b32_e32 v42, 0
	v_mov_b32_e32 v43, 0
	v_mov_b32_e32 v36, 0
	v_mov_b32_e32 v37, 0
	v_mov_b32_e32 v38, 0
	v_mov_b32_e32 v39, 0
	v_readlane_b32 s10, v247, 3
	v_readlane_b32 s11, v247, 4
	v_readlane_b32 s14, v247, 7
	v_readlane_b32 s15, v247, 8
	v_readlane_b32 s16, v247, 9
	v_readlane_b32 s17, v247, 10
	v_readlane_b32 s18, v247, 11
	v_readlane_b32 s19, v247, 12
	v_readlane_b32 s20, v247, 13
	v_readlane_b32 s21, v247, 14
	v_readlane_b32 s22, v247, 15
	v_readlane_b32 s23, v247, 16
	s_and_saveexec_b64 s[6:7], vcc
	s_cbranch_execz .LBB0_362
	v_readlane_b32 s8, v247, 1
	s_movk_i32 s0, 0x7fff
	v_readlane_b32 s9, v247, 2
	v_readlane_b32 s13, v247, 6
	v_add_u32_e32 v0, 0xffff8001, v64
	v_cmp_gt_i32_e64 s[0:1], s0, v64
	v_readlane_b32 s12, v247, 5
	v_mov_b32_e32 v2, s13
	v_mov_b32_e32 v3, s9
	v_cndmask_b32_e64 v1, 0, v77, s[0:1]
	v_cndmask_b32_e64 v0, v0, v76, s[0:1]
	v_cndmask_b32_e64 v3, v2, v3, s[0:1]
	v_mov_b32_e32 v2, s12
	v_mov_b32_e32 v36, s8
	v_cndmask_b32_e64 v2, v2, v36, s[0:1]
	v_lshlrev_b64 v[0:1], 12, v[0:1]
	v_mov_b32_e32 v67, 0
	v_lshl_add_u64 v[0:1], v[2:3], 0, v[0:1]
	v_lshl_add_u64 v[36:37], v[0:1], 0, v[66:67]
	global_load_dwordx4 v[0:3], v[36:37], off nt
	global_load_dwordx4 v[44:47], v[36:37], off offset:1024 nt
	global_load_dwordx4 v[40:43], v[36:37], off offset:2048 nt
	s_nop 0
	global_load_dwordx4 v[36:39], v[36:37], off offset:3072 nt
	v_readlane_b32 s10, v247, 3
	v_readlane_b32 s11, v247, 4
	v_readlane_b32 s14, v247, 7
	v_readlane_b32 s15, v247, 8
	v_readlane_b32 s16, v247, 9
	v_readlane_b32 s17, v247, 10
	v_readlane_b32 s18, v247, 11
	v_readlane_b32 s19, v247, 12
	v_readlane_b32 s20, v247, 13
	v_readlane_b32 s21, v247, 14
	v_readlane_b32 s22, v247, 15
	v_readlane_b32 s23, v247, 16

.LBB0_367:
	s_or_b64 exec, exec, s[10:11]
	v_add_u32_e32 v48, 2, v80
	v_cmp_lt_i32_e32 vcc, v48, v82
	v_mov_b32_e32 v48, v0
	v_mov_b32_e32 v49, v1
	v_mov_b32_e32 v50, v2
	v_mov_b32_e32 v51, v3
	v_mov_b32_e32 v52, v44
	v_mov_b32_e32 v53, v45
	v_mov_b32_e32 v54, v46
	v_mov_b32_e32 v55, v47
	v_mov_b32_e32 v56, v40
	v_mov_b32_e32 v57, v41
	v_mov_b32_e32 v58, v42
	v_mov_b32_e32 v59, v43
	v_mov_b32_e32 v60, v36
	v_mov_b32_e32 v61, v37
	v_mov_b32_e32 v62, v38
	v_mov_b32_e32 v63, v39
	s_and_saveexec_b64 s[10:11], vcc
	s_cbranch_execz .LBB0_364
	v_readlane_b32 s16, v247, 1
	v_add_u32_e32 v50, 0xffff8002, v80
	v_lshl_add_u64 v[48:49], v[78:79], 0, s[8:9]
	v_cmp_gt_i32_e32 vcc, s12, v81
	v_readlane_b32 s17, v247, 2
	v_readlane_b32 s21, v247, 6
	v_cndmask_b32_e32 v48, v50, v48, vcc
	v_readlane_b32 s20, v247, 5
	v_mov_b32_e32 v50, s21
	v_mov_b32_e32 v51, s17
	v_cndmask_b32_e32 v49, 0, v49, vcc
	v_cndmask_b32_e32 v51, v50, v51, vcc
	v_mov_b32_e32 v50, s20
	v_mov_b32_e32 v52, s16
	v_cndmask_b32_e32 v50, v50, v52, vcc
	v_lshlrev_b64 v[48:49], 12, v[48:49]
	v_lshl_add_u64 v[48:49], v[50:51], 0, v[48:49]
	v_lshl_add_u64 v[60:61], v[48:49], 0, v[66:67]
	global_load_dwordx4 v[48:51], v[60:61], off nt
	global_load_dwordx4 v[52:55], v[60:61], off offset:1024 nt
	global_load_dwordx4 v[56:59], v[60:61], off offset:2048 nt
	s_nop 0
	global_load_dwordx4 v[60:63], v[60:61], off offset:3072 nt
	v_readlane_b32 s18, v247, 3
	v_readlane_b32 s19, v247, 4
	v_readlane_b32 s22, v247, 7
	v_readlane_b32 s23, v247, 8
	v_readlane_b32 s24, v247, 9
	v_readlane_b32 s25, v247, 10
	v_readlane_b32 s26, v247, 11
	v_readlane_b32 s27, v247, 12
	v_readlane_b32 s28, v247, 13
	v_readlane_b32 s29, v247, 14
	v_readlane_b32 s30, v247, 15
	v_readlane_b32 s31, v247, 16
	s_branch .LBB0_364

.LBB0_1006:
	s_or_b64 exec, exec, s[0:1]
	v_ashrrev_i32_e32 v117, 31, v116
	v_readlane_b32 s68, v247, 1
	v_lshlrev_b64 v[122:123], 12, v[116:117]
	v_readlane_b32 s69, v247, 2
	v_mov_b32_e32 v105, v81
	v_lshlrev_b64 v[118:119], 11, v[116:117]
	v_lshl_add_u64 v[50:51], s[68:69], 0, v[122:123]
	v_lshl_add_u64 v[50:51], v[50:51], 0, v[104:105]
	global_load_dwordx4 v[76:79], v[50:51], off nt
	global_load_dwordx4 v[72:75], v[50:51], off offset:1024 nt
	global_load_dwordx4 v[68:71], v[50:51], off offset:2048 nt
	global_load_dwordx4 v[64:67], v[50:51], off offset:3072 nt
	v_lshl_add_u64 v[50:51], s[22:23], 0, v[118:119]
	v_lshlrev_b32_e32 v120, 1, v48
	v_mov_b32_e32 v121, v81
	v_lshl_add_u64 v[132:133], v[116:117], 2, s[44:45]
	v_lshl_add_u64 v[48:49], v[50:51], 0, v[120:121]
	global_load_dword v87, v[132:133], off nt
	global_load_dwordx2 v[130:131], v[48:49], off nt
	global_load_dwordx2 v[128:129], v[48:49], off offset:512 nt
	global_load_dwordx2 v[126:127], v[48:49], off offset:1024 nt
	global_load_dwordx2 v[124:125], v[48:49], off offset:1536 nt
	v_add_u32_e32 v106, 1, v116
	v_cmp_lt_i32_e32 vcc, v106, v138
	v_ashrrev_i32_e32 v107, 31, v106
	v_readlane_b32 s70, v247, 3
	v_readlane_b32 s71, v247, 4
	v_readlane_b32 s72, v247, 5
	v_readlane_b32 s73, v247, 6
	v_readlane_b32 s74, v247, 7
	v_readlane_b32 s75, v247, 8
	v_readlane_b32 s76, v247, 9
	v_readlane_b32 s77, v247, 10
	v_readlane_b32 s78, v247, 11
	v_readlane_b32 s79, v247, 12
	v_readlane_b32 s80, v247, 13
	v_readlane_b32 s81, v247, 14
	v_readlane_b32 s82, v247, 15
	v_readlane_b32 s83, v247, 16
	s_and_saveexec_b64 s[0:1], vcc
	s_cbranch_execz .LBB0_1008
	v_readlane_b32 s68, v247, 1
	v_lshlrev_b64 v[48:49], 12, v[106:107]
	v_readlane_b32 s69, v247, 2
	v_mov_b32_e32 v105, 0
	v_lshlrev_b64 v[108:109], 11, v[106:107]
	v_lshl_add_u64 v[48:49], s[68:69], 0, v[48:49]
	v_lshl_add_u64 v[48:49], v[48:49], 0, v[104:105]
	v_lshl_add_u64 v[108:109], s[22:23], 0, v[108:109]
	v_mov_b32_e32 v121, v105
	global_load_dwordx4 v[60:63], v[48:49], off nt
	global_load_dwordx4 v[56:59], v[48:49], off offset:1024 nt
	global_load_dwordx4 v[52:55], v[48:49], off offset:2048 nt
	s_nop 0
	global_load_dwordx4 v[48:51], v[48:49], off offset:3072 nt
	s_nop 0
	global_load_dword v81, v[132:133], off offset:4 nt
	v_lshl_add_u64 v[108:109], v[108:109], 0, v[120:121]
	global_load_dwordx2 v[114:115], v[108:109], off nt
	global_load_dwordx2 v[112:113], v[108:109], off offset:512 nt
	global_load_dwordx2 v[110:111], v[108:109], off offset:1024 nt
	s_nop 0
	global_load_dwordx2 v[108:109], v[108:109], off offset:1536 nt
	v_readlane_b32 s70, v247, 3
	v_readlane_b32 s71, v247, 4
	v_readlane_b32 s72, v247, 5
	v_readlane_b32 s73, v247, 6
	v_readlane_b32 s74, v247, 7
	v_readlane_b32 s75, v247, 8
	v_readlane_b32 s76, v247, 9
	v_readlane_b32 s77, v247, 10
	v_readlane_b32 s78, v247, 11
	v_readlane_b32 s79, v247, 12
	v_readlane_b32 s80, v247, 13
	v_readlane_b32 s81, v247, 14
	v_readlane_b32 s82, v247, 15
	v_readlane_b32 s83, v247, 16

.LBB0_1013:
	s_or_b64 exec, exec, s[24:25]
	v_add_u32_e32 v64, 1, v106
	v_cmp_lt_i32_e32 vcc, v64, v138
	v_mov_b64_e32 v[78:79], v[50:51]
	v_mov_b64_e32 v[74:75], v[54:55]
	v_mov_b64_e32 v[70:71], v[58:59]
	v_mov_b64_e32 v[66:67], v[62:63]
	v_mov_b64_e32 v[134:135], v[106:107]
	v_mov_b64_e32 v[76:77], v[48:49]
	v_mov_b64_e32 v[72:73], v[52:53]
	v_mov_b64_e32 v[68:69], v[56:57]
	v_mov_b64_e32 v[64:65], v[60:61]
	v_mov_b64_e32 v[132:133], v[108:109]
	v_mov_b64_e32 v[130:131], v[110:111]
	v_mov_b64_e32 v[128:129], v[112:113]
	v_mov_b64_e32 v[126:127], v[114:115]
	v_mov_b32_e32 v87, v81
	s_and_saveexec_b64 s[24:25], vcc
	s_cbranch_execz .LBB0_1010
	global_load_dwordx4 v[64:67], v[124:125], off nt
	global_load_dwordx4 v[68:71], v[124:125], off offset:1024 nt
	global_load_dwordx4 v[72:75], v[124:125], off offset:2048 nt
	global_load_dwordx4 v[76:79], v[124:125], off offset:3072 nt
	global_load_dword v87, v[122:123], off nt
	global_load_dwordx2 v[126:127], v[116:117], off nt
	global_load_dwordx2 v[128:129], v[116:117], off offset:512 nt
	global_load_dwordx2 v[130:131], v[116:117], off offset:1024 nt
	global_load_dwordx2 v[132:133], v[116:117], off offset:1536 nt
	v_ashrrev_i32_e32 v135, 31, v106
	v_mov_b32_e32 v134, v106
	s_branch .LBB0_1010

.LBB0_1019:
	v_ashrrev_i32_e32 v55, 31, v54
	v_lshlrev_b64 v[138:139], 12, v[54:55]
	v_lshl_add_u64 v[130:131], v[94:95], 0, v[138:139]
	v_lshl_add_u64 v[134:135], v[80:81], 0, v[138:139]
	global_load_dwordx4 v[106:109], v[134:135], off nt
	global_load_dwordx4 v[110:113], v[130:131], off nt
	global_load_dwordx4 v[114:117], v[130:131], off offset:1024 nt
	global_load_dwordx4 v[118:121], v[134:135], off offset:1024 nt
	global_load_dwordx4 v[122:125], v[134:135], off offset:2048 nt
	global_load_dwordx4 v[126:129], v[130:131], off offset:2048 nt
	s_nop 0
	global_load_dwordx4 v[130:133], v[130:131], off offset:3072 nt
	s_nop 0
	global_load_dwordx4 v[134:137], v[134:135], off offset:3072 nt
	v_lshl_add_u64 v[150:151], v[92:93], 0, v[138:139]
	global_load_dwordx4 v[138:141], v[150:151], off nt
	global_load_dwordx4 v[142:145], v[150:151], off offset:1024 nt
	global_load_dwordx4 v[146:149], v[150:151], off offset:2048 nt
	s_nop 0
	global_load_dwordx4 v[150:153], v[150:151], off offset:3072 nt
	s_mov_b64 s[10:11], -1
	s_waitcnt vmcnt(10)
	v_pk_add_f32 v[108:109], v[112:113], v[108:109]
	v_pk_add_f32 v[106:107], v[110:111], v[106:107]
	s_waitcnt vmcnt(8)
	v_pk_add_f32 v[112:113], v[114:115], v[118:119]
	v_pk_add_f32 v[110:111], v[116:117], v[120:121]
	s_waitcnt vmcnt(6)
	v_pk_add_f32 v[114:115], v[128:129], v[124:125]
	v_pk_add_f32 v[116:117], v[126:127], v[122:123]
	s_waitcnt vmcnt(4)
	v_pk_add_f32 v[120:121], v[130:131], v[134:135]
	v_mov_b32_e32 v124, v107
	v_mov_b32_e32 v125, v113
	v_pk_add_f32 v[118:119], v[132:133], v[136:137]
	v_mov_b32_e32 v122, v106
	v_mov_b32_e32 v123, v112
	v_mov_b32_e32 v132, v117
	v_mov_b32_e32 v133, v121
	v_pk_mul_f32 v[124:125], v[124:125], v[124:125]
	v_mov_b32_e32 v126, v108
	v_mov_b32_e32 v127, v110
	v_mov_b32_e32 v130, v116
	v_mov_b32_e32 v131, v120
	v_pk_mul_f32 v[132:133], v[132:133], v[132:133]
	v_pk_fma_f32 v[122:123], v[122:123], v[122:123], v[124:125]
	v_mov_b32_e32 v128, v109
	v_mov_b32_e32 v129, v111
	v_mov_b32_e32 v134, v114
	v_mov_b32_e32 v135, v118
	v_pk_fma_f32 v[124:125], v[130:131], v[130:131], v[132:133]
	v_pk_fma_f32 v[122:123], v[126:127], v[126:127], v[122:123]
	v_mov_b32_e32 v136, v115
	v_mov_b32_e32 v137, v119
	v_pk_fma_f32 v[124:125], v[134:135], v[134:135], v[124:125]
	v_pk_fma_f32 v[122:123], v[128:129], v[128:129], v[122:123]
	v_pk_fma_f32 v[124:125], v[136:137], v[136:137], v[124:125]
	v_add_f32_e32 v55, v122, v123
	v_add_f32_e32 v55, v55, v124
	v_add_f32_e32 v55, v55, v125
	ds_bpermute_b32 v122, v99, v55
	s_waitcnt lgkmcnt(0)
	v_add_f32_e32 v55, v55, v122
	ds_bpermute_b32 v122, v100, v55
	s_waitcnt lgkmcnt(0)
	v_add_f32_e32 v55, v55, v122
	ds_bpermute_b32 v122, v101, v55
	s_waitcnt lgkmcnt(0)
	v_add_f32_e32 v55, v55, v122
	ds_bpermute_b32 v122, v102, v55
	s_waitcnt lgkmcnt(0)
	v_add_f32_e32 v55, v55, v122
	ds_bpermute_b32 v122, v103, v55
	s_waitcnt lgkmcnt(0)
	v_add_f32_e32 v55, v55, v122
	ds_bpermute_b32 v122, v104, v55
	s_waitcnt lgkmcnt(0)
	v_add_f32_e32 v55, v55, v122
	v_fmamk_f32 v55, v55, 0x3a800000, v105
	v_mul_f32_e32 v122, 0x4b800000, v55
	v_cmp_gt_f32_e32 vcc, s3, v55
	s_nop 1
	v_cndmask_b32_e32 v55, v55, v122, vcc
	v_rsq_f32_e32 v55, v55
	s_nop 0
	v_mul_f32_e32 v122, 0x45800000, v55
	v_cndmask_b32_e32 v122, v55, v122, vcc
	v_pk_mul_f32 v[106:107], v[106:107], v[122:123] op_sel_hi:[1,0]
	v_pk_mul_f32 v[112:113], v[112:113], v[122:123] op_sel_hi:[1,0]
	v_pk_mul_f32 v[116:117], v[116:117], v[122:123] op_sel_hi:[1,0]
	v_pk_mul_f32 v[120:121], v[120:121], v[122:123] op_sel_hi:[1,0]
	s_waitcnt vmcnt(3)
	v_pk_fma_f32 v[106:107], v[16:17], v[106:107], v[138:139]
	s_waitcnt vmcnt(2)
	v_pk_fma_f32 v[112:113], v[24:25], v[112:113], v[142:143]
	v_pk_mul_f32 v[108:109], v[108:109], v[122:123] op_sel_hi:[1,0]
	v_pk_mul_f32 v[110:111], v[110:111], v[122:123] op_sel_hi:[1,0]
	s_waitcnt vmcnt(1)
	v_pk_fma_f32 v[116:117], v[32:33], v[116:117], v[146:147]
	s_waitcnt vmcnt(0)
	v_pk_fma_f32 v[120:121], v[40:41], v[120:121], v[150:151]
	v_mov_b32_e32 v124, v107
	v_mov_b32_e32 v125, v113
	v_pk_mul_f32 v[114:115], v[114:115], v[122:123] op_sel_hi:[1,0]
	v_pk_mul_f32 v[118:119], v[118:119], v[122:123] op_sel_hi:[1,0]
	v_pk_fma_f32 v[108:109], v[18:19], v[108:109], v[140:141]
	v_pk_fma_f32 v[110:111], v[26:27], v[110:111], v[144:145]
	v_mov_b32_e32 v122, v106
	v_mov_b32_e32 v123, v112
	v_mov_b32_e32 v132, v121
	v_mov_b32_e32 v133, v117
	v_pk_mul_f32 v[124:125], v[124:125], v[124:125]
	v_pk_fma_f32 v[114:115], v[34:35], v[114:115], v[148:149]
	v_pk_fma_f32 v[118:119], v[42:43], v[118:119], v[152:153]
	v_mov_b32_e32 v126, v108
	v_mov_b32_e32 v127, v110
	v_mov_b32_e32 v130, v120
	v_mov_b32_e32 v131, v116
	v_pk_mul_f32 v[132:133], v[132:133], v[132:133]
	v_pk_fma_f32 v[122:123], v[122:123], v[122:123], v[124:125]
	v_mov_b32_e32 v128, v109
	v_mov_b32_e32 v129, v111
	v_mov_b32_e32 v134, v118
	v_mov_b32_e32 v135, v114
	v_pk_fma_f32 v[124:125], v[130:131], v[130:131], v[132:133]
	v_pk_fma_f32 v[122:123], v[126:127], v[126:127], v[122:123]
	v_mov_b32_e32 v136, v119
	v_mov_b32_e32 v137, v115
	v_pk_fma_f32 v[124:125], v[134:135], v[134:135], v[124:125]
	v_pk_fma_f32 v[122:123], v[128:129], v[128:129], v[122:123]
	v_pk_fma_f32 v[124:125], v[136:137], v[136:137], v[124:125]
	v_add_f32_e32 v55, v122, v123
	v_add_f32_e32 v55, v125, v55
	v_add_f32_e32 v55, v124, v55
	ds_bpermute_b32 v122, v99, v55
	v_add_u32_e32 v123, 1, v54
	v_add_u32_e32 v54, 0x8001, v54
	v_cmp_ge_i32_e64 s[0:1], v54, v98
	s_or_b64 s[6:7], s[0:1], s[6:7]
	s_waitcnt lgkmcnt(0)
	v_add_f32_e32 v55, v55, v122
	ds_bpermute_b32 v122, v100, v55
	s_waitcnt lgkmcnt(0)
	v_add_f32_e32 v55, v55, v122
	ds_bpermute_b32 v122, v101, v55
	s_waitcnt lgkmcnt(0)
	v_add_f32_e32 v55, v55, v122
	ds_bpermute_b32 v122, v102, v55
	s_waitcnt lgkmcnt(0)
	v_add_f32_e32 v55, v55, v122
	ds_bpermute_b32 v122, v103, v55
	s_waitcnt lgkmcnt(0)
	v_add_f32_e32 v55, v55, v122
	ds_bpermute_b32 v122, v104, v55
	s_waitcnt lgkmcnt(0)
	v_add_f32_e32 v55, v55, v122
	v_fmamk_f32 v55, v55, 0x3a800000, v105
	v_mul_f32_e32 v122, 0x4b800000, v55
	v_cmp_gt_f32_e32 vcc, s3, v55
	s_nop 1
	v_cndmask_b32_e32 v55, v55, v122, vcc
	v_rsq_f32_e32 v55, v55
	s_nop 0
	v_mul_f32_e32 v54, 0x45800000, v55
	v_cndmask_b32_e32 v54, v55, v54, vcc
	v_pk_mul_f32 v[106:107], v[106:107], v[54:55] op_sel_hi:[1,0]
	v_pk_mul_f32 v[108:109], v[108:109], v[54:55] op_sel_hi:[1,0]
	v_pk_mul_f32 v[112:113], v[112:113], v[54:55] op_sel_hi:[1,0]
	v_pk_mul_f32 v[110:111], v[110:111], v[54:55] op_sel_hi:[1,0]
	v_pk_mul_f32 v[116:117], v[116:117], v[54:55] op_sel_hi:[1,0]
	v_pk_mul_f32 v[114:115], v[114:115], v[54:55] op_sel_hi:[1,0]
	v_pk_mul_f32 v[120:121], v[120:121], v[54:55] op_sel_hi:[1,0]
	v_pk_mul_f32 v[54:55], v[118:119], v[54:55] op_sel_hi:[1,0]
	v_pk_fma_f32 v[108:109], v[22:23], v[108:109], v[2:3]
	v_pk_fma_f32 v[106:107], v[20:21], v[106:107], v[0:1]
	v_pk_fma_f32 v[110:111], v[30:31], v[110:111], v[10:11]
	v_pk_fma_f32 v[112:113], v[28:29], v[112:113], v[8:9]
	v_pk_fma_f32 v[114:115], v[38:39], v[114:115], v[6:7]
	v_pk_fma_f32 v[116:117], v[36:37], v[116:117], v[4:5]
	v_pk_fma_f32 v[54:55], v[46:47], v[54:55], v[14:15]
	v_pk_fma_f32 v[118:119], v[44:45], v[120:121], v[12:13]
	v_cvt_pk_bf16_f32 v106, v106, v107
	v_cvt_pk_bf16_f32 v107, v108, v109
	v_cvt_pk_bf16_f32 v108, v112, v113
	v_cvt_pk_bf16_f32 v109, v110, v111
	v_cvt_pk_bf16_f32 v110, v116, v117
	v_cvt_pk_bf16_f32 v111, v114, v115
	v_cvt_pk_bf16_f32 v112, v118, v119
	v_cvt_pk_bf16_f32 v113, v54, v55
	global_store_dwordx2 v[96:97], v[106:107], off offset:-1024
	global_store_dwordx2 v[96:97], v[108:109], off offset:-512
	global_store_dwordx2 v[96:97], v[110:111], off
	global_store_dwordx2 v[96:97], v[112:113], off offset:512
	v_lshl_add_u64 v[96:97], v[96:97], 0, s[8:9]
	v_mov_b32_e32 v54, v123
	s_andn2_b64 exec, exec, s[6:7]
	s_cbranch_execz .LBB0_1022
.LBB0_1020:
	s_and_b64 vcc, exec, s[10:11]
	s_cbranch_vccnz .LBB0_1019
	global_load_dwordx4 v[16:19], v[66:67], off nt
	global_load_dwordx4 v[20:23], v[68:69], off nt
	global_load_dwordx4 v[24:27], v[72:73], off nt
	global_load_dwordx4 v[28:31], v[74:75], off nt
	global_load_dwordx4 v[32:35], v[78:79], off nt
	global_load_dwordx4 v[36:39], v[82:83], off nt
	global_load_dwordx4 v[40:43], v[86:87], off nt
	global_load_dwordx4 v[44:47], v[88:89], off nt
	global_load_dwordx4 v[106:109], v[48:49], off nt
	global_load_dwordx4 v[110:113], v[50:51], off nt
	global_load_dwordx4 v[114:117], v[52:53], off nt
	global_load_dwordx4 v[118:121], v[56:57], off nt
	global_load_dwordx4 v[122:125], v[58:59], off nt
	global_load_dwordx4 v[126:129], v[60:61], off nt
	global_load_dwordx4 v[0:3], v[70:71], off nt
	global_load_dwordx4 v[130:133], v[62:63], off nt
	global_load_dwordx4 v[4:7], v[84:85], off nt
	global_load_dwordx4 v[134:137], v[64:65], off nt
	global_load_dwordx4 v[8:11], v[76:77], off nt
	global_load_dwordx4 v[12:15], v[90:91], off nt
	s_waitcnt vmcnt(19)
	v_pk_mul_f32 v[18:19], v[18:19], 0.5 op_sel_hi:[1,0]
	v_pk_mul_f32 v[16:17], v[16:17], 0.5 op_sel_hi:[1,0]
	s_waitcnt vmcnt(18)
	v_pk_add_f32 v[22:23], v[22:23], 1.0 op_sel_hi:[1,0]
	v_pk_add_f32 v[20:21], v[20:21], 1.0 op_sel_hi:[1,0]
	s_waitcnt vmcnt(17)
	v_pk_mul_f32 v[26:27], v[26:27], 0.5 op_sel_hi:[1,0]
	v_pk_mul_f32 v[24:25], v[24:25], 0.5 op_sel_hi:[1,0]
	s_waitcnt vmcnt(16)
	v_pk_add_f32 v[30:31], v[30:31], 1.0 op_sel_hi:[1,0]
	v_pk_add_f32 v[28:29], v[28:29], 1.0 op_sel_hi:[1,0]
	s_waitcnt vmcnt(15)
	v_pk_mul_f32 v[34:35], v[34:35], 0.5 op_sel_hi:[1,0]
	v_pk_mul_f32 v[32:33], v[32:33], 0.5 op_sel_hi:[1,0]
	s_waitcnt vmcnt(14)
	v_pk_add_f32 v[38:39], v[38:39], 1.0 op_sel_hi:[1,0]
	v_pk_add_f32 v[36:37], v[36:37], 1.0 op_sel_hi:[1,0]
	s_waitcnt vmcnt(13)
	v_pk_mul_f32 v[42:43], v[42:43], 0.5 op_sel_hi:[1,0]
	v_pk_mul_f32 v[40:41], v[40:41], 0.5 op_sel_hi:[1,0]
	s_waitcnt vmcnt(12)
	v_pk_add_f32 v[46:47], v[46:47], 1.0 op_sel_hi:[1,0]
	v_pk_add_f32 v[44:45], v[44:45], 1.0 op_sel_hi:[1,0]
	s_waitcnt vmcnt(11)
	v_pk_mul_f32 v[18:19], v[18:19], v[108:109]
	v_pk_mul_f32 v[16:17], v[16:17], v[106:107]
	s_waitcnt vmcnt(10)
	v_pk_mul_f32 v[22:23], v[112:113], v[22:23]
	v_pk_mul_f32 v[20:21], v[110:111], v[20:21]
	s_waitcnt vmcnt(9)
	v_pk_mul_f32 v[26:27], v[26:27], v[116:117]
	v_pk_mul_f32 v[24:25], v[24:25], v[114:115]
	s_waitcnt vmcnt(8)
	v_pk_mul_f32 v[30:31], v[120:121], v[30:31]
	v_pk_mul_f32 v[28:29], v[118:119], v[28:29]
	s_waitcnt vmcnt(7)
	v_pk_mul_f32 v[34:35], v[34:35], v[124:125]
	v_pk_mul_f32 v[32:33], v[32:33], v[122:123]
	s_waitcnt vmcnt(6)
	v_pk_mul_f32 v[38:39], v[128:129], v[38:39]
	v_pk_mul_f32 v[36:37], v[126:127], v[36:37]
	s_waitcnt vmcnt(4)
	v_pk_mul_f32 v[42:43], v[42:43], v[132:133]
	v_pk_mul_f32 v[40:41], v[40:41], v[130:131]
	s_waitcnt vmcnt(2)
	v_pk_mul_f32 v[46:47], v[136:137], v[46:47]
	v_pk_mul_f32 v[44:45], v[134:135], v[44:45]
	s_branch .LBB0_1019

.LBB0_1674:
	s_or_b64 exec, exec, s[0:1]
	v_ashrrev_i32_e32 v93, 31, v92
	v_readlane_b32 s48, v247, 33
	v_lshlrev_b64 v[74:75], 12, v[92:93]
	v_readlane_b32 s62, v247, 47
	v_readlane_b32 s63, v247, 48
	v_lshlrev_b32_e32 v72, 1, v72
	v_lshlrev_b64 v[96:97], 11, v[92:93]
	v_lshl_add_u64 v[74:75], s[62:63], 0, v[74:75]
	v_lshl_add_u64 v[94:95], v[74:75], 0, v[72:73]
	v_lshl_add_u64 v[74:75], s[8:9], 0, v[96:97]
	v_lshl_add_u64 v[114:115], v[92:93], 2, s[10:11]
	v_lshl_add_u64 v[74:75], v[74:75], 0, v[72:73]
	global_load_dwordx2 v[112:113], v[94:95], off nt
	global_load_dwordx2 v[110:111], v[94:95], off offset:512 nt
	global_load_dwordx2 v[108:109], v[94:95], off offset:1024 nt
	global_load_dwordx2 v[104:105], v[94:95], off offset:1536 nt
	global_load_dword v49, v[114:115], off nt
	global_load_dwordx2 v[106:107], v[74:75], off nt
	global_load_dwordx2 v[102:103], v[74:75], off offset:512 nt
	global_load_dwordx2 v[100:101], v[74:75], off offset:1024 nt
	global_load_dwordx2 v[98:99], v[74:75], off offset:1536 nt
	v_add_u32_e32 v74, 1, v92
	v_cmp_lt_i32_e32 vcc, v74, v120
	v_ashrrev_i32_e32 v75, 31, v74
	v_readlane_b32 s49, v247, 34
	v_readlane_b32 s50, v247, 35
	v_readlane_b32 s51, v247, 36
	v_readlane_b32 s52, v247, 37
	v_readlane_b32 s53, v247, 38
	v_readlane_b32 s54, v247, 39
	v_readlane_b32 s55, v247, 40
	v_readlane_b32 s56, v247, 41
	v_readlane_b32 s57, v247, 42
	v_readlane_b32 s58, v247, 43
	v_readlane_b32 s59, v247, 44
	v_readlane_b32 s60, v247, 45
	v_readlane_b32 s61, v247, 46
	s_and_saveexec_b64 s[0:1], vcc
	s_cbranch_execz .LBB0_1676
	v_readlane_b32 s48, v247, 33
	v_lshlrev_b64 v[76:77], 12, v[74:75]
	v_readlane_b32 s62, v247, 47
	v_readlane_b32 s63, v247, 48
	v_mov_b32_e32 v73, 0
	v_readlane_b32 s49, v247, 34
	v_lshl_add_u64 v[76:77], s[62:63], 0, v[76:77]
	v_lshl_add_u64 v[76:77], v[76:77], 0, v[72:73]
	global_load_dwordx2 v[90:91], v[76:77], off nt
	global_load_dwordx2 v[88:89], v[76:77], off offset:512 nt
	global_load_dwordx2 v[84:85], v[76:77], off offset:1024 nt
	global_load_dwordx2 v[82:83], v[76:77], off offset:1536 nt
	global_load_dword v55, v[114:115], off offset:4 nt
	v_lshlrev_b64 v[76:77], 11, v[74:75]
	v_lshl_add_u64 v[76:77], s[8:9], 0, v[76:77]
	v_lshl_add_u64 v[114:115], v[76:77], 0, v[72:73]
	global_load_dwordx2 v[86:87], v[114:115], off nt
	global_load_dwordx2 v[80:81], v[114:115], off offset:512 nt
	global_load_dwordx2 v[78:79], v[114:115], off offset:1024 nt
	global_load_dwordx2 v[76:77], v[114:115], off offset:1536 nt
	v_readlane_b32 s50, v247, 35
	v_readlane_b32 s51, v247, 36
	v_readlane_b32 s52, v247, 37
	v_readlane_b32 s53, v247, 38
	v_readlane_b32 s54, v247, 39
	v_readlane_b32 s55, v247, 40
	v_readlane_b32 s56, v247, 41
	v_readlane_b32 s57, v247, 42
	v_readlane_b32 s58, v247, 43
	v_readlane_b32 s59, v247, 44
	v_readlane_b32 s60, v247, 45
	v_readlane_b32 s61, v247, 46
	s_waitcnt vmcnt(4)
	v_mov_b32_e32 v73, v55

.LBB0_1681:
	s_or_b64 exec, exec, s[0:1]
	v_add_u32_e32 v74, 1, v74
	v_cmp_lt_i32_e32 vcc, v74, v120
	v_cmp_ge_i32_e64 s[0:1], v74, v120
	v_mov_b64_e32 v[110:111], v[82:83]
	v_mov_b64_e32 v[108:109], v[84:85]
	v_mov_b64_e32 v[106:107], v[88:89]
	v_mov_b64_e32 v[104:105], v[90:91]
	v_mov_b64_e32 v[118:119], v[76:77]
	v_mov_b64_e32 v[116:117], v[78:79]
	v_mov_b64_e32 v[114:115], v[80:81]
	v_mov_b64_e32 v[112:113], v[86:87]
	v_mov_b32_e32 v55, v73
	s_and_saveexec_b64 s[18:19], vcc
	s_cbranch_execz .LBB0_1678
	v_lshl_add_u64 v[112:113], v[100:101], 0, v[94:95]
	v_lshl_add_u64 v[110:111], v[102:103], 0, v[94:95]
	v_add_co_u32_e32 v118, vcc, 0x2000000, v112
	global_load_dwordx2 v[104:105], v[110:111], off nt
	global_load_dwordx2 v[106:107], v[110:111], off offset:512 nt
	global_load_dwordx2 v[108:109], v[110:111], off offset:1024 nt
	s_nop 0
	global_load_dwordx2 v[110:111], v[110:111], off offset:1536 nt
	s_nop 0
	global_load_dword v55, v[92:93], off nt
	v_addc_co_u32_e32 v119, vcc, 0, v113, vcc
	global_load_dwordx2 v[112:113], v[118:119], off nt
	global_load_dwordx2 v[114:115], v[118:119], off offset:512 nt
	global_load_dwordx2 v[116:117], v[118:119], off offset:1024 nt
	s_nop 0
	global_load_dwordx2 v[118:119], v[118:119], off offset:1536 nt
	s_branch .LBB0_1678

.LBB0_1911:
	s_or_b64 exec, exec, s[0:1]
	v_ashrrev_i32_e32 v53, 31, v52
	v_readlane_b32 s48, v247, 33
	v_lshlrev_b64 v[34:35], 12, v[52:53]
	v_readlane_b32 s62, v247, 47
	v_readlane_b32 s63, v247, 48
	v_lshlrev_b32_e32 v32, 1, v32
	v_lshl_add_u64 v[74:75], v[52:53], 2, s[8:9]
	v_lshl_add_u64 v[56:57], s[62:63], 0, v[34:35]
	v_lshlrev_b64 v[34:35], 11, v[52:53]
	v_lshl_add_u64 v[34:35], s[22:23], 0, v[34:35]
	v_lshl_add_u64 v[60:61], v[56:57], 0, v[32:33]
	v_lshl_add_u64 v[34:35], v[34:35], 0, v[32:33]
	global_load_dwordx2 v[72:73], v[60:61], off nt
	global_load_dwordx2 v[70:71], v[60:61], off offset:512 nt
	global_load_dwordx2 v[68:69], v[60:61], off offset:1024 nt
	global_load_dwordx2 v[64:65], v[60:61], off offset:1536 nt
	global_load_dword v17, v[74:75], off nt
	global_load_dwordx2 v[66:67], v[34:35], off nt
	global_load_dwordx2 v[62:63], v[34:35], off offset:512 nt
	global_load_dwordx2 v[58:59], v[34:35], off offset:1024 nt
	global_load_dwordx2 v[54:55], v[34:35], off offset:1536 nt
	v_add_u32_e32 v34, 1, v52
	v_cmp_lt_i32_e32 vcc, v34, v78
	v_ashrrev_i32_e32 v35, 31, v34
	v_readlane_b32 s49, v247, 34
	v_readlane_b32 s50, v247, 35
	v_readlane_b32 s51, v247, 36
	v_readlane_b32 s52, v247, 37
	v_readlane_b32 s53, v247, 38
	v_readlane_b32 s54, v247, 39
	v_readlane_b32 s55, v247, 40
	v_readlane_b32 s56, v247, 41
	v_readlane_b32 s57, v247, 42
	v_readlane_b32 s58, v247, 43
	v_readlane_b32 s59, v247, 44
	v_readlane_b32 s60, v247, 45
	v_readlane_b32 s61, v247, 46
	s_and_saveexec_b64 s[0:1], vcc
	s_cbranch_execz .LBB0_1913
	v_readlane_b32 s4, v247, 33
	v_lshlrev_b64 v[36:37], 12, v[34:35]
	v_readlane_b32 s18, v247, 47
	v_readlane_b32 s19, v247, 48
	v_mov_b32_e32 v33, 0
	v_readlane_b32 s5, v247, 34
	v_lshl_add_u64 v[36:37], s[18:19], 0, v[36:37]
	v_lshl_add_u64 v[36:37], v[36:37], 0, v[32:33]
	global_load_dwordx2 v[50:51], v[36:37], off nt
	global_load_dwordx2 v[48:49], v[36:37], off offset:512 nt
	global_load_dwordx2 v[44:45], v[36:37], off offset:1024 nt
	global_load_dwordx2 v[42:43], v[36:37], off offset:1536 nt
	global_load_dword v21, v[74:75], off offset:4 nt
	v_lshlrev_b64 v[36:37], 11, v[34:35]
	v_lshl_add_u64 v[36:37], s[22:23], 0, v[36:37]
	v_lshl_add_u64 v[74:75], v[36:37], 0, v[32:33]
	global_load_dwordx2 v[46:47], v[74:75], off nt
	global_load_dwordx2 v[40:41], v[74:75], off offset:512 nt
	global_load_dwordx2 v[38:39], v[74:75], off offset:1024 nt
	global_load_dwordx2 v[36:37], v[74:75], off offset:1536 nt
	v_readlane_b32 s6, v247, 35
	v_readlane_b32 s7, v247, 36
	v_readlane_b32 s8, v247, 37
	v_readlane_b32 s9, v247, 38
	v_readlane_b32 s10, v247, 39
	v_readlane_b32 s11, v247, 40
	v_readlane_b32 s12, v247, 41
	v_readlane_b32 s13, v247, 42
	v_readlane_b32 s14, v247, 43
	v_readlane_b32 s15, v247, 44
	v_readlane_b32 s16, v247, 45
	v_readlane_b32 s17, v247, 46
	s_waitcnt vmcnt(4)
	v_mov_b32_e32 v33, v21

.LBB0_1918:
	s_or_b64 exec, exec, s[0:1]
	v_add_u32_e32 v34, 1, v34
	v_cmp_lt_i32_e32 vcc, v34, v78
	v_cmp_ge_i32_e64 s[0:1], v34, v78
	v_mov_b64_e32 v[68:69], v[42:43]
	v_mov_b64_e32 v[66:67], v[44:45]
	v_mov_b64_e32 v[64:65], v[48:49]
	v_mov_b64_e32 v[62:63], v[50:51]
	v_mov_b64_e32 v[76:77], v[36:37]
	v_mov_b64_e32 v[74:75], v[38:39]
	v_mov_b64_e32 v[72:73], v[40:41]
	v_mov_b64_e32 v[70:71], v[46:47]
	v_mov_b32_e32 v21, v33
	s_and_saveexec_b64 s[10:11], vcc
	s_cbranch_execz .LBB0_1915
	v_lshl_add_u64 v[70:71], v[60:61], 0, v[56:57]
	global_load_dwordx2 v[62:63], v[70:71], off nt
	global_load_dwordx2 v[64:65], v[70:71], off offset:512 nt
	global_load_dwordx2 v[66:67], v[70:71], off offset:1024 nt
	global_load_dwordx2 v[68:69], v[70:71], off offset:1536 nt
	global_load_dword v21, v[52:53], off nt
	v_lshl_add_u64 v[70:71], v[58:59], 0, v[56:57]
	v_add_co_u32_e32 v82, vcc, 0xc600000, v70
	s_nop 1
	v_addc_co_u32_e32 v83, vcc, 0, v71, vcc
	global_load_dwordx2 v[70:71], v[82:83], off nt
	global_load_dwordx2 v[72:73], v[82:83], off offset:512 nt
	global_load_dwordx2 v[74:75], v[82:83], off offset:1024 nt
	global_load_dwordx2 v[76:77], v[82:83], off offset:1536 nt
	s_branch .LBB0_1915
